# plus: lru pass 1 item loop loads the next item rows into spare registers during the current item
# baseline (speedup 1.0000x reference)
; template <bool P3>
; __device__ __forceinline__ void lru_pass(KA a, int layer, unsigned char* lds, const int tid_, const int bid_) {
;     const int tid = tid_, lane = tid & 63, wave = tid >> 6, tl = tid >> 3, sub = tid & 7, fr = lane & 15, fq = lane >> 4;
;     unsigned char* ws = a->ws;
;     float* XCF = (float*)lds; float* AL = XCF + 8448; bf16_t* XCB = (bf16_t*)(AL + 8448); float* CP = (float*)((unsigned char*)XCB + 17408);
;     float* lcw = CP + 1024;
;     float* SEG = lcw + 640;
;     const bf16_t* XB = (const bf16_t*)(ws + WS_XB);
;     float* AGGA = (float*)(ws + WS_AGGA); float* AGGB = (float*)(ws + WS_AGGB);
;     int n_loaded = -1;
;     bf16x8 Ba[4], Bx[4]; float ba = 0.f, bx = 0.f, spl = 0.f;
; #pragma unroll
;     for (int ks = 0; ks < 4; ++ks) { Ba[ks] = (bf16x8){0, 0, 0, 0, 0, 0, 0, 0}; Bx[ks] = (bf16x8){0, 0, 0, 0, 0, 0, 0, 0}; }
;     for (int item = bid_; item < 2048; item += gridDim.x) {
;         const int c = item >> 3, n = item & 7;
;         const int tg = c * 64 + tl, s = tg & (SEQ_ - 1), ch0 = n * 128 + 16 * sub;
;         u32x4 xr[4][2];
; #pragma unroll
;         for (int j = 0; j < 4; ++j) { const int rowi = (s - 3 + j >= 0) ? tg - 3 + j : tg; const bf16_t* row = XB + (size_t)rowi * 1024 + ch0; xr[j][0] = *(const u32x4*)row; xr[j][1] = *(const u32x4*)(row + 8); }
.LBB0_224:
	v_readlane_b32 s8, v255, 34
	v_readlane_b32 s9, v255, 35
	s_and_b64 vcc, exec, s[8:9]
	s_cbranch_vccnz .LBB0_239
	s_add_u32 s8, s4, 0x100000
	s_addc_u32 s9, s5, 0
	s_add_u32 s10, s4, 0x15800000
	s_addc_u32 s11, s5, 0
	s_add_u32 s12, s4, 0x200000
	s_addc_u32 s13, s5, 0
	s_lshl_b32 s14, s6, 10
	v_readlane_b32 s20, v255, 27
	s_movk_i32 s7, 0xa0
	s_ashr_i32 s15, s14, 31
	v_readlane_b32 s21, v255, 28
	v_cmp_gt_i32_e32 vcc, s7, v198
	s_and_b64 s[16:17], s[20:21], exec
	s_mov_b32 s7, 0x300000
	v_and_b32_e32 v0, 31, v198
	s_cselect_b32 s7, s7, 0x9000000
	v_bfe_u32 v5, v198, 4, 2
	v_lshlrev_b32_e32 v4, 2, v0
	v_lshlrev_b32_e32 v7, 4, v0
	s_add_u32 s16, s4, s7
	v_ashrrev_i32_e32 v0, 2, v198
	s_addc_u32 s17, s5, 0
	v_and_or_b32 v91, v0, -16, v111
	v_lshlrev_b32_e32 v0, 4, v5
	v_lshl_add_u64 v[86:87], s[16:17], 0, v[0:1]
	s_and_b64 s[16:17], s[20:21], exec
	s_mov_b32 s7, 0x380000
	s_cselect_b32 s7, s7, 0x9080000
	s_add_u32 s16, s4, s7
	v_lshl_add_u32 v2, s6, 2, v146
	s_addc_u32 s17, s5, 0
	v_ashrrev_i32_e32 v3, 31, v2
	v_lshl_add_u64 v[88:89], s[16:17], 0, v[0:1]
	s_movk_i32 s16, 0x210
	v_lshlrev_b64 v[84:85], 12, v[2:3]
	v_readlane_b32 s18, v255, 9
	v_lshlrev_b32_e32 v2, 2, v145
	v_readlane_b32 s7, v255, 10
	v_mul_lo_u32 v3, v144, s16
	v_add_u32_e32 v121, s18, v2
	v_add_u32_e32 v120, s7, v2
	v_add3_u32 v122, 0, v3, v2
	v_lshlrev_b32_e32 v2, 1, v145
	v_readlane_b32 s7, v255, 11
	v_add_u32_e32 v6, s18, v115
	v_mul_u32_u24_e32 v9, 0x110, v111
	v_add3_u32 v123, s7, v113, v2
	v_add_u32_e32 v8, s7, v0
	s_movk_i32 s7, 0x80
	v_and_b32_e32 v0, 0x7f, v198
	v_cmp_gt_i32_e64 s[42:43], s7, v198
	v_mad_u32_u24 v2, v5, s16, v91
	s_movk_i32 s7, 0x84
	v_lshl_add_u32 v124, v2, 2, 0
	v_mad_u64_u32 v[2:3], s[16:17], v99, s7, v[0:1]
	v_lshl_add_u32 v125, v2, 2, 0
	v_or_b32_e32 v2, 15, v144
	v_mad_u64_u32 v[2:3], s[16:17], v2, s7, v[0:1]
	v_lshl_add_u32 v126, v2, 2, 0
	v_mov_b32_e32 v2, v1
	v_mov_b32_e32 v3, v1
	v_mov_b32_e32 v0, v1
	v_lshlrev_b32_e32 v92, 2, v4
	v_add_u32_e32 v127, v6, v7
	v_add_u32_e32 v128, v8, v9
	v_mov_b64_e32 v[6:7], v[2:3]
	v_mov_b64_e32 v[14:15], v[2:3]
	v_mov_b64_e32 v[22:23], v[2:3]
	v_mov_b64_e32 v[30:31], v[2:3]
	v_mov_b64_e32 v[10:11], v[2:3]
	v_mov_b64_e32 v[18:19], v[2:3]
	v_mov_b64_e32 v[26:27], v[2:3]
	v_mov_b64_e32 v[34:35], v[2:3]
	v_cmp_lt_i32_e64 s[40:41], 3, v146
	v_ashrrev_i32_e32 v199, 31, v198
	v_mov_b32_e32 v93, 0
	s_mov_b32 s20, -1
	v_mov_b64_e32 v[4:5], v[0:1]
	v_mov_b64_e32 v[12:13], v[0:1]
	v_mov_b64_e32 v[20:21], v[0:1]
	v_mov_b64_e32 v[28:29], v[0:1]
	v_mov_b64_e32 v[8:9], v[0:1]
	v_mov_b64_e32 v[16:17], v[0:1]
	v_mov_b64_e32 v[24:25], v[0:1]
	v_mov_b64_e32 v[32:33], v[0:1]
	v_mov_b32_e32 v129, 0
	v_mov_b32_e32 v130, 0
	s_mov_b32 s7, s28
	s_mov_b32 s100, s7
	s_ashr_i32 s101, s100, 3
	s_and_b32 s100, s100, 7
	s_lshl_b32 s100, s100, 7
	v_lshl_add_u32 v208, s101, 6, v144
	v_and_b32_e32 v209, 0xfff, v208
	v_or_b32_e32 v210, s100, v145
	v_lshlrev_b32_e32 v210, 1, v210
	v_mov_b32_e32 v211, 0
	v_mov_b32_e32 v215, 0
	v_lshl_add_u64 v[212:213], s[10:11], 0, v[210:211]
	v_add_u32_e32 v214, -3, v208
	v_cmp_gt_u32_e64 s[100:101], 3, v209
	s_nop 1
	v_cndmask_b32_e64 v214, v214, v208, s[100:101]
	v_lshlrev_b32_e32 v214, 11, v214
	v_lshl_add_u64 v[216:217], v[212:213], 0, v[214:215]
	global_load_dwordx4 v[160:163], v[216:217], off offset:16
	global_load_dwordx4 v[164:167], v[216:217], off
	v_add_u32_e32 v214, -2, v208
	v_cmp_gt_u32_e64 s[100:101], 2, v209
	s_nop 1
	v_cndmask_b32_e64 v214, v214, v208, s[100:101]
	v_lshlrev_b32_e32 v214, 11, v214
	v_lshl_add_u64 v[216:217], v[212:213], 0, v[214:215]
	global_load_dwordx4 v[168:171], v[216:217], off offset:16
	global_load_dwordx4 v[172:175], v[216:217], off
	v_add_u32_e32 v214, -1, v208
	v_cmp_eq_u32_e64 s[100:101], 0, v209
	s_nop 1
	v_cndmask_b32_e64 v214, v214, v208, s[100:101]
	v_lshlrev_b32_e32 v214, 11, v214
	v_lshl_add_u64 v[216:217], v[212:213], 0, v[214:215]
	global_load_dwordx4 v[176:179], v[216:217], off offset:16
	global_load_dwordx4 v[180:183], v[216:217], off
	v_lshlrev_b32_e32 v214, 11, v208
	v_lshl_add_u64 v[216:217], v[212:213], 0, v[214:215]
	global_load_dwordx4 v[200:203], v[216:217], off offset:16
	global_load_dwordx4 v[204:207], v[216:217], off
	s_branch .LBB0_227

; template <bool P3>
; __device__ __forceinline__ void lru_pass(KA a, int layer, unsigned char* lds, const int tid_, const int bid_) {
;     ...
;     for (int item = bid_; item < 2048; item += gridDim.x) {
;         const int c = item >> 3, n = item & 7;
;         const int tg = c * 64 + tl, s = tg & (SEQ_ - 1), ch0 = n * 128 + 16 * sub;
;         u32x4 xr[4][2];
; #pragma unroll
;         for (int j = 0; j < 4; ++j) { const int rowi = (s - 3 + j >= 0) ? tg - 3 + j : tg; const bf16_t* row = XB + (size_t)rowi * 1024 + ch0; xr[j][0] = *(const u32x4*)row; xr[j][1] = *(const u32x4*)(row + 8); }
.LBB0_227:
	s_ashr_i32 s16, s7, 3
	v_lshl_add_u32 v2, s16, 6, v144
	s_and_b32 s17, s7, 7
	v_and_b32_e32 v80, 0xfff, v2
	s_lshl_b32 s29, s17, 7
	v_add_u32_e32 v3, -3, v2
	v_cmp_gt_u32_e64 s[44:45], 3, v80
	v_or_b32_e32 v0, s29, v145
	v_lshlrev_b32_e32 v0, 1, v0
	v_cndmask_b32_e64 v36, v3, v2, s[44:45]
	v_ashrrev_i32_e32 v37, 31, v36
	v_lshl_add_u64 v[48:49], s[10:11], 0, v[0:1]
	v_lshlrev_b64 v[36:37], 11, v[36:37]
	v_lshl_add_u64 v[40:41], v[48:49], 0, v[36:37]
	v_add_u32_e32 v0, -2, v2
	v_cmp_gt_u32_e64 s[44:45], 2, v80
	v_cndmask_b32_e64 v40, v0, v2, s[44:45]
	v_ashrrev_i32_e32 v41, 31, v40
	v_lshlrev_b64 v[40:41], 11, v[40:41]
	v_lshl_add_u64 v[44:45], v[48:49], 0, v[40:41]
	v_cmp_ne_u32_e64 s[44:45], 0, v80
	v_subbrev_co_u32_e64 v44, s[44:45], 0, v2, s[44:45]
	v_ashrrev_i32_e32 v45, 31, v44
	v_ashrrev_i32_e32 v3, 31, v2
	v_lshlrev_b64 v[44:45], 11, v[44:45]
	v_lshlrev_b64 v[2:3], 11, v[2:3]
	v_lshl_add_u64 v[50:51], v[48:49], 0, v[44:45]
	v_lshl_add_u64 v[2:3], v[48:49], 0, v[2:3]
	s_waitcnt vmcnt(0)
	v_mov_b32_e32 v36, v160
	v_mov_b32_e32 v37, v161
	v_mov_b32_e32 v38, v162
	v_mov_b32_e32 v39, v163
	v_mov_b32_e32 v52, v164
	v_mov_b32_e32 v53, v165
	v_mov_b32_e32 v54, v166
	v_mov_b32_e32 v55, v167
	v_mov_b32_e32 v40, v168
	v_mov_b32_e32 v41, v169
	v_mov_b32_e32 v42, v170
	v_mov_b32_e32 v43, v171
	v_mov_b32_e32 v56, v172
	v_mov_b32_e32 v57, v173
	v_mov_b32_e32 v58, v174
	v_mov_b32_e32 v59, v175
	v_mov_b32_e32 v44, v176
	v_mov_b32_e32 v45, v177
	v_mov_b32_e32 v46, v178
	v_mov_b32_e32 v47, v179
	v_mov_b32_e32 v60, v180
	v_mov_b32_e32 v61, v181
	v_mov_b32_e32 v62, v182
	v_mov_b32_e32 v63, v183
	v_mov_b32_e32 v48, v200
	v_mov_b32_e32 v49, v201
	v_mov_b32_e32 v50, v202
	v_mov_b32_e32 v51, v203
	v_mov_b32_e32 v64, v204
	v_mov_b32_e32 v65, v205
	v_mov_b32_e32 v66, v206
	v_mov_b32_e32 v67, v207
	s_add_i32 s100, s7, s98
	s_ashr_i32 s101, s100, 3
	s_and_b32 s100, s100, 7
	s_lshl_b32 s100, s100, 7
	v_lshl_add_u32 v208, s101, 6, v144
	v_and_b32_e32 v209, 0xfff, v208
	v_or_b32_e32 v210, s100, v145
	v_lshlrev_b32_e32 v210, 1, v210
	v_mov_b32_e32 v211, 0
	v_mov_b32_e32 v215, 0
	v_lshl_add_u64 v[212:213], s[10:11], 0, v[210:211]
	v_add_u32_e32 v214, -3, v208
	v_cmp_gt_u32_e64 s[100:101], 3, v209
	s_nop 1
	v_cndmask_b32_e64 v214, v214, v208, s[100:101]
	v_lshlrev_b32_e32 v214, 11, v214
	v_lshl_add_u64 v[216:217], v[212:213], 0, v[214:215]
	global_load_dwordx4 v[160:163], v[216:217], off offset:16
	global_load_dwordx4 v[164:167], v[216:217], off
	v_add_u32_e32 v214, -2, v208
	v_cmp_gt_u32_e64 s[100:101], 2, v209
	s_nop 1
	v_cndmask_b32_e64 v214, v214, v208, s[100:101]
	v_lshlrev_b32_e32 v214, 11, v214
	v_lshl_add_u64 v[216:217], v[212:213], 0, v[214:215]
	global_load_dwordx4 v[168:171], v[216:217], off offset:16
	global_load_dwordx4 v[172:175], v[216:217], off
	v_add_u32_e32 v214, -1, v208
	v_cmp_eq_u32_e64 s[100:101], 0, v209
	s_nop 1
	v_cndmask_b32_e64 v214, v214, v208, s[100:101]
	v_lshlrev_b32_e32 v214, 11, v214
	v_lshl_add_u64 v[216:217], v[212:213], 0, v[214:215]
	global_load_dwordx4 v[176:179], v[216:217], off offset:16
	global_load_dwordx4 v[180:183], v[216:217], off
	v_lshlrev_b32_e32 v214, 11, v208
	v_lshl_add_u64 v[216:217], v[212:213], 0, v[214:215]
	global_load_dwordx4 v[200:203], v[216:217], off offset:16
	global_load_dwordx4 v[204:207], v[216:217], off
	s_cmp_eq_u32 s17, s20
	s_cbranch_scc1 .LBB0_237
	s_and_saveexec_b64 s[18:19], vcc
	s_cbranch_execz .LBB0_234
	s_and_saveexec_b64 s[20:21], s[40:41]
	s_xor_b64 s[20:21], exec, s[20:21]
	s_cbranch_execz .LBB0_231
	s_load_dwordx2 s[30:31], s[2:3], 0x40
	s_lshl_b64 s[44:45], s[14:15], 2
	s_waitcnt lgkmcnt(0)
	s_add_u32 s44, s30, s44
	s_addc_u32 s45, s31, s45

; __global__ void __launch_bounds__(512, 2) mega(Args a_) {
	.amdhsa_kernel _Z4mega4Args
		.amdhsa_group_segment_fixed_size 0
		.amdhsa_private_segment_fixed_size 0
		.amdhsa_kernarg_size 448
		.amdhsa_user_sgpr_count 2
		.amdhsa_user_sgpr_dispatch_ptr 0
		.amdhsa_user_sgpr_queue_ptr 0
		.amdhsa_user_sgpr_kernarg_segment_ptr 1
		.amdhsa_user_sgpr_dispatch_id 0
		.amdhsa_user_sgpr_kernarg_preload_length 0
		.amdhsa_user_sgpr_kernarg_preload_offset 0
		.amdhsa_user_sgpr_private_segment_size 0
		.amdhsa_uses_dynamic_stack 0
		.amdhsa_enable_private_segment 0
		.amdhsa_system_sgpr_workgroup_id_x 1
		.amdhsa_system_sgpr_workgroup_id_y 0
		.amdhsa_system_sgpr_workgroup_id_z 0
		.amdhsa_system_sgpr_workgroup_info 0
		.amdhsa_system_vgpr_workitem_id 2
		.amdhsa_next_free_vgpr 256
		.amdhsa_next_free_sgpr 102
		.amdhsa_accum_offset 256
		.amdhsa_reserve_vcc 1
		.amdhsa_float_round_mode_32 0
		.amdhsa_float_round_mode_16_64 0
		.amdhsa_float_denorm_mode_32 3
		.amdhsa_float_denorm_mode_16_64 3
		.amdhsa_dx10_clamp 1
		.amdhsa_ieee_mode 1
		.amdhsa_fp16_overflow 0
		.amdhsa_tg_split 0
		.amdhsa_exception_fp_ieee_invalid_op 0
		.amdhsa_exception_fp_denorm_src 0
		.amdhsa_exception_fp_ieee_div_zero 0
		.amdhsa_exception_fp_ieee_overflow 0
		.amdhsa_exception_fp_ieee_underflow 0
		.amdhsa_exception_fp_ieee_inexact 0
		.amdhsa_exception_int_div_zero 0
	.end_amdhsa_kernel

; __global__ void __launch_bounds__(512, 2) mega(Args a_) {
amdhsa.kernels:
  - .agpr_count:     0
    .args:
      - .offset:         0
        .size:           192
        .value_kind:     by_value
      - .offset:         192
        .size:           4
        .value_kind:     hidden_block_count_x
      - .offset:         196
        .size:           4
        .value_kind:     hidden_block_count_y
      - .offset:         200
        .size:           4
        .value_kind:     hidden_block_count_z
      - .offset:         204
        .size:           2
        .value_kind:     hidden_group_size_x
      - .offset:         206
        .size:           2
        .value_kind:     hidden_group_size_y
      - .offset:         208
        .size:           2
        .value_kind:     hidden_group_size_z
      - .offset:         210
        .size:           2
        .value_kind:     hidden_remainder_x
      - .offset:         212
        .size:           2
        .value_kind:     hidden_remainder_y
      - .offset:         214
        .size:           2
        .value_kind:     hidden_remainder_z
      - .offset:         232
        .size:           8
        .value_kind:     hidden_global_offset_x
      - .offset:         240
        .size:           8
        .value_kind:     hidden_global_offset_y
      - .offset:         248
        .size:           8
        .value_kind:     hidden_global_offset_z
      - .offset:         256
        .size:           2
        .value_kind:     hidden_grid_dims
      - .offset:         280
        .size:           8
        .value_kind:     hidden_multigrid_sync_arg
      - .offset:         312
        .size:           4
        .value_kind:     hidden_dynamic_lds_size
    .group_segment_fixed_size: 0
    .kernarg_segment_align: 8
    .kernarg_segment_size: 448
    .language:       OpenCL C
    .language_version:
      - 2
      - 0
    .max_flat_workgroup_size: 512
    .name:           _Z4mega4Args
    .private_segment_fixed_size: 0
    .sgpr_count:     108
    .sgpr_spill_count: 113
    .symbol:         _Z4mega4Args.kd
    .uniform_work_group_size: 1
    .uses_dynamic_stack: false
    .vgpr_count:     256
    .vgpr_spill_count: 0
    .wavefront_size: 64
